# v72 + diff loops: next-step K-fragment addresses, next-tile V read base and DMA offsets computed inside the dependent QK MFMA chain gaps (cost-weighted VALU spacing, sec 7.5)
# baseline (speedup 1.0000x reference)
; DI float bf2f(unsigned short h) { return __uint_as_float((unsigned)h << 16); }
; template <int DQK, int MODE, int LDQ, int LDK, int LDV> ...
;     ...
;     float l_reg = 0.f; f32x16 o[4];
; #pragma unroll
;     for (int d = 0; d < 4; ++d)
; #pragma unroll
;         for (int r = 0; r < 16; ++r) o[d][r] = 0.f;
;     int kgo[NKP], vgo[2];
; #pragma unroll
;     for (int i = 0; i < NKP; ++i) { const int L = (wid + 8 * i) * 64 + lane, row = L / CPR, slot = L % CPR, cc = (slot & ~7) | ((slot & 7) ^ ((row >> 1) & 7)); kgo[i] = row * LDK + cc * 8; }
; #pragma unroll
;     for (int i = 0; i < 2; ++i) { const int L = (2 * wid + i) * 64 + lane, st = L >> 5, w5 = L & 31, kk = (st >> 2) * 8 + (w5 >> 2), c = (st & 3) * 32 + (w5 & 3) * 8;
;         const int k = (kk & ~0xC) | ((kk & 4) << 1) | ((kk & 8) >> 1); vgo[i] = k * LDV + c; }
;     ...
;     ATT_DMA_K(0); ATT_DMA_K(1); ATT_DMA_V(0, 0); ATT_DMA_K(2); ATT_DMA_V(1, 1);
;     bf16x8 qr[ND0];
;     { const bf16_t* Qw = Qb + (size_t)(wid * 32 + r32) * LDQ + hi * 8;
; #pragma unroll
;       for (int d0 = 0; d0 < ND0; ++d0) qr[d0] = *(const bf16x8*)(Qw + d0 * 16);
;       if constexpr (MODE == 0) {
;           float ss = 0.f;
; #pragma unroll
;           for (int d0 = 0; d0 < ND0; ++d0)
; #pragma unroll
;               for (int j = 0; j < 8; ++j) { const float f = bf2f((unsigned short)qr[d0][j]); ss += f * f; }
;           ss = swap_sum(ss);
;           const float rstd = rsqrtf(ss * (1.f / DQK) + EPS) * C;
; #pragma unroll
;           for (int d0 = 0; d0 < ND0; ++d0) { const float* g = gq + d0 * 16 + hi * 8;
;               { float f[8]; _Pragma("unroll") for (int j = 0; j < 8; ++j) f[j] = bf2f((unsigned short)qr[d0][j]) * rstd * g[j];
;                 u32x4 w = {cvtpk(f[0], f[1]), cvtpk(f[2], f[3]), cvtpk(f[4], f[5]), cvtpk(f[6], f[7])}; qr[d0] = __builtin_bit_cast(bf16x8, w); asm volatile("" ::: "memory"); } }
;       } }
;     const int qlo = q0 + wid * 32, qpos = qlo + r32;
;     const int tL = MODE == 0 ? 0 : (qlo >= 191 ? (qlo - 127) >> 6 : 0), tR = MODE == 0 ? NT : min(NT, (qlo + 222) >> 6);
;     float fL = 1.f, fR = 1.f; if constexpr (MODE != 0) { fL = __builtin_amdgcn_exp2f(bt[0]); fR = __builtin_amdgcn_exp2f(-bt[448]); }
;     ...
;     const int vbase = (int)(unsigned)(size_t)lds + V_OFF + v_rd_base(lane);
.LBB0_1919:
	s_lshl_b32 s87, s86, 7
	s_and_b32 s54, s0, 0xffffffc0
	s_min_i32 s97, s58, 64
	s_and_b32 s92, s73, 0xf00
	s_cmp_gt_i32 s55, 0
	s_cselect_b64 s[4:5], -1, 0
	s_add_i32 s93, 0, 0x18000
	s_add_i32 s1, s92, s94
	s_add_u32 s90, s2, s84
	v_add_lshl_u32 v2, s1, v2, 2
	s_addc_u32 s91, s3, 0
	v_readlane_b32 s1, v255, 6
	s_add_u32 s2, s1, s90
	s_addc_u32 s3, s76, s91
	s_add_i32 s7, s7, s6
	v_lshl_add_u64 v[100:101], v[0:1], 1, s[2:3]
	v_subrev_u32_e32 v100, s34, v100
	v_add3_u32 v0, s7, v6, v4
	v_lshl_or_b32 v0, v0, 11, v3
	v_and_b32_e32 v7, 63, v7
	v_add_u32_e32 v0, v0, v5
	s_add_u32 s2, s77, s90
	v_exp_f32_e32 v112, v9
	v_lshlrev_b32_e32 v8, 3, v7
	v_lshlrev_b32_e32 v9, 4, v7
	v_lshlrev_b32_e32 v7, 1, v7
	v_ashrrev_i32_e32 v1, 31, v0
	s_addc_u32 s3, s78, s91
	v_exp_f32_e64 v113, -v10
	v_and_b32_e32 v7, 32, v7
	v_lshl_add_u64 v[102:103], v[0:1], 1, s[2:3]
	v_subrev_u32_e32 v102, s34, v102
	v_add_u32_e32 v0, 64, v0
	v_and_b32_e32 v9, 0xc0, v9
	v_and_or_b32 v7, v8, s66, v7
	v_sub_u32_e32 v2, v130, v2
	v_ashrrev_i32_e32 v1, 31, v0
	v_mov_b32_e32 v14, v131
	v_mov_b32_e32 v15, v131
	v_add3_u32 v106, v9, s93, v7
	v_add_u32_e32 v119, 0, v2
	v_lshl_add_u64 v[104:105], v[0:1], 1, s[2:3]
	v_subrev_u32_e32 v104, s34, v104
	v_mov_b32_e32 v0, v131
	v_mov_b32_e32 v1, v131
	v_mov_b32_e32 v2, v131
	v_mov_b32_e32 v3, v131
	v_mov_b32_e32 v4, v131
	v_mov_b32_e32 v5, v131
	v_mov_b32_e32 v6, v131
	v_mov_b32_e32 v7, v131
	v_mov_b32_e32 v8, v131
	v_mov_b32_e32 v9, v131
	v_mov_b32_e32 v10, v131
	v_mov_b32_e32 v11, v131
	v_mov_b32_e32 v12, v131
	v_mov_b32_e32 v13, v131
	v_mov_b64_e32 v[62:63], v[14:15]
	v_mov_b64_e32 v[46:47], v[14:15]
	v_mov_b64_e32 v[30:31], v[14:15]
	s_mov_b32 s0, 1
	s_mov_b32 s23, 0
	s_mov_b32 s96, 2
	s_sub_i32 s62, 0, s55
	s_sub_i32 s6, 0, s97
	v_mov_b32_e32 v120, 0
	s_movk_i32 s7, 0xc300
	s_movk_i32 s22, 0x6000
	s_add_i32 s98, s55, 1
	s_add_i32 s99, s97, 1
	s_sub_i32 s101, s97, s55
	s_max_i32 s100, s101, 0
	v_mov_b32_e32 v196, v107
	v_mov_b32_e32 v197, v108
	v_mov_b32_e32 v198, v109
	v_mov_b32_e32 v199, v110
	v_mov_b64_e32 v[60:61], v[12:13]
	v_mov_b64_e32 v[58:59], v[10:11]
	v_mov_b64_e32 v[56:57], v[8:9]
	v_mov_b64_e32 v[54:55], v[6:7]
	v_mov_b64_e32 v[52:53], v[4:5]
	v_mov_b64_e32 v[50:51], v[2:3]
	v_mov_b64_e32 v[48:49], v[0:1]
	v_mov_b64_e32 v[44:45], v[12:13]
	v_mov_b64_e32 v[42:43], v[10:11]
	v_mov_b64_e32 v[40:41], v[8:9]
	v_mov_b64_e32 v[38:39], v[6:7]
	v_mov_b64_e32 v[36:37], v[4:5]
	v_mov_b64_e32 v[34:35], v[2:3]
	v_mov_b64_e32 v[32:33], v[0:1]
	v_mov_b64_e32 v[28:29], v[12:13]
	v_mov_b64_e32 v[26:27], v[10:11]
	v_mov_b64_e32 v[24:25], v[8:9]
	v_mov_b64_e32 v[22:23], v[6:7]
	v_mov_b64_e32 v[20:21], v[4:5]
	v_mov_b64_e32 v[18:19], v[2:3]
	v_mov_b64_e32 v[16:17], v[0:1]
	s_mov_b32 s64, 1
	v_mov_b32_e32 v121, v106
	s_cmp_lt_u32 s33, 0x100
	s_cbranch_scc1 .LBB0_1920
	s_waitcnt vmcnt(3)
	s_barrier

; #define SBAR() __builtin_amdgcn_sched_barrier(0)
; #define ATT_DMA_K(t) do { const bf16_t* kg_ = Kh + (size_t)(t) * 64 * LDK; LAS unsigned char* sb_ = lds + ((t) & 3) * KBUF; \
;     _Pragma("unroll") for (int i_ = 0; i_ < NKP; ++i_) __builtin_amdgcn_global_load_lds((const unsigned*)(kg_ + kgo[i_]), (LAS unsigned*)(sb_ + (wid + 8 * i_) * 1024), 16, 0, 0); } while (0)
; #define ATT_DMA_V(t, vs) do { const bf16_t* vg_ = Vh + (size_t)(t) * 64 * LDV; LAS unsigned char* sb_ = lds + V_OFF + (vs) * SHM_V; \
;     _Pragma("unroll") for (int i_ = 0; i_ < 2; ++i_) __builtin_amdgcn_global_load_lds((const unsigned*)(vg_ + vgo[i_]), (LAS unsigned*)(sb_ + (2 * wid + i_) * 1024), 16, 0, 0); } while (0)
; #define ATT_SEG(t) do { if constexpr (MODE != 0) { if (((t) == tL && tL > 0) || (t) == tR) { const float f_ = (t) == tR ? fR : fL; l_reg *= f_; \
;     _Pragma("unroll") for (int d = 0; d < 4; ++d) _Pragma("unroll") for (int r = 0; r < 16; ++r) o[d][r] *= f_; } } } while (0)
; #define ATT_BIAS(P, t, half) do { if constexpr (MODE != 0) { if ((t) >= tL && (t) < tR) { const LAS float* bp_ = bt + ((t) * 64 + (half) * 32 - qpos + 224 + 4 * hi);     \
;     _Pragma("unroll") for (int r = 0; r < 16; ++r) P[r] += bp_[(r & 3) + 8 * (r >> 2)]; } } } while (0)
; #define ATT_TOP(N) do { asm volatile("s_waitcnt vmcnt(%0)" :: "n"(N) : "memory"); __builtin_amdgcn_s_barrier(); asm volatile("" ::: "memory"); } while (0)
; template <int DQK, int MODE, int LDQ, int LDK, int LDV> ...
;     ...
;     f32x16 pA, pB; bf16x8 pa0, pa1;
;     int v0 = 0, v1 = 1, v2 = 2;
;     ATT_TOP(NKP + 2);
;     { bf16x8 kf[NDA]; k_reads<DQK, 0, NDA>(kf, lds, 0, r32, hi); ATT_LGKM0(); qk_mma<0, NDA>(pA, kf, qr);
;       if constexpr (ND0 > NDA) { bf16x8 kg[ND0 - NDA]; k_reads<DQK, NDA, ND0>(kg, lds, 0, r32, hi); ATT_LGKM0(); qk_mma<NDA, ND0>(pA, kg, qr); }
;       ATT_BIAS(pA, 0, 0); }
;     if (wid >= 4) __builtin_amdgcn_s_setprio(1);
;     for (int j = 0; j < NT; ++j) {
;         if (j + 2 < NT) ATT_TOP(NKP + 2); else ATT_TOP(0);
;         if (j + 3 < NT) ATT_DMA_K(j + 3);
;         if (j + 2 < NT) ATT_DMA_V(j + 2, v2);
;         ATT_SEG(j); SBAR();
;         ATT_STEP(pA, pB, 0, v0, true, 1, j);
;         ATT_STEP(pB, pA, 1, v0, (j + 1 < NT), 0, j + 1);
;         { const int t_ = v0; v0 = v1; v1 = v2; v2 = t_; }
;     }
.Lhw_d0_b_n1922:
	ds_read_b128 v[122:125], v196 offset:4096
	ds_read_b128 v[132:135], v197 offset:4096
	s_lshl_b32 s2, s1, 14
	ds_read_b128 v[136:139], v198 offset:4096
	ds_read_b128 v[140:143], v199 offset:4096
	ds_read_b64_tr_b16 v[144:145], v121 offset:0
	ds_read_b64_tr_b16 v[146:147], v121 offset:0x800
	ds_read_b64_tr_b16 v[148:149], v121 offset:0x1000
	ds_read_b64_tr_b16 v[150:151], v121 offset:0x1800
	ds_read_b64_tr_b16 v[152:153], v121 offset:0x200
	ds_read_b64_tr_b16 v[154:155], v121 offset:0xa00
	ds_read_b64_tr_b16 v[156:157], v121 offset:0x1200
	ds_read_b64_tr_b16 v[158:159], v121 offset:0x1a00
	ds_read_b64_tr_b16 v[162:163], v121 offset:0x400
	ds_read_b64_tr_b16 v[164:165], v121 offset:0xc00
	ds_read_b64_tr_b16 v[166:167], v121 offset:0x1400
	ds_read_b64_tr_b16 v[168:169], v121 offset:0x1c00
	ds_read_b64_tr_b16 v[170:171], v121 offset:0x600
	ds_read_b64_tr_b16 v[172:173], v121 offset:0xe00
	ds_read_b64_tr_b16 v[174:175], v121 offset:0x1600
	ds_read_b64_tr_b16 v[176:177], v121 offset:0x1e00
	s_setprio 2
	v_exp_f32_e32 v64, v64
	v_exp_f32_e32 v65, v65
	v_exp_f32_e32 v66, v66
	v_exp_f32_e32 v67, v67
	v_exp_f32_e32 v68, v68
	v_exp_f32_e32 v69, v69
	v_add_f32_e32 v126, v65, v64
	v_exp_f32_e32 v70, v70
	v_add_f32_e32 v126, v66, v126
	v_exp_f32_e32 v71, v71
	v_add_f32_e32 v126, v67, v126
	v_exp_f32_e32 v72, v72
	v_add_f32_e32 v126, v68, v126
	v_exp_f32_e32 v73, v73
	v_add_f32_e32 v126, v69, v126
	v_exp_f32_e32 v74, v74
	v_add_f32_e32 v126, v70, v126
	v_exp_f32_e32 v75, v75
	v_add_f32_e32 v126, v71, v126
	v_exp_f32_e32 v76, v76
	v_add_f32_e32 v126, v72, v126
	v_exp_f32_e32 v77, v77
	v_add_f32_e32 v126, v73, v126
	v_exp_f32_e32 v78, v78
	v_add_f32_e32 v126, v74, v126
	v_exp_f32_e32 v79, v79
	v_add_f32_e32 v126, v75, v126
	v_add_f32_e32 v126, v76, v126
	v_add_f32_e32 v126, v77, v126
	v_add_f32_e32 v126, v78, v126
	v_add_f32_e32 v126, v79, v126
	v_add_f32_e32 v120, v126, v120
	v_cvt_pk_bf16_f32 v64, v64, v65
	v_cvt_pk_bf16_f32 v65, v66, v67
	v_cvt_pk_bf16_f32 v66, v68, v69
	v_cvt_pk_bf16_f32 v67, v70, v71
	v_cvt_pk_bf16_f32 v68, v72, v73
	v_cvt_pk_bf16_f32 v69, v74, v75
	v_cvt_pk_bf16_f32 v70, v76, v77
	v_cvt_pk_bf16_f32 v71, v78, v79
	s_waitcnt lgkmcnt(0)
	s_setprio 1
	v_mfma_f32_32x32x16_bf16 v[0:15], v[64:67], v[144:147], v[0:15]
	s_add_i32 s74, s22, 0xffffc000
	s_and_b32 s74, s74, 0x6000
	s_sub_i32 s3, s0, s98
	s_cmp_lt_u32 s3, s100
	v_mfma_f32_32x32x16_bf16 v[48:63], v[64:67], v[152:155], v[48:63]
	v_mfma_f32_32x32x16_bf16 v[32:47], v[64:67], v[162:165], v[32:47]
	v_mfma_f32_32x32x16_bf16 v[16:31], v[64:67], v[170:173], v[16:31]
	v_mfma_f32_32x32x16_bf16 v[0:15], v[68:71], v[148:151], v[0:15]
	v_mfma_f32_32x32x16_bf16 v[48:63], v[68:71], v[156:159], v[48:63]
	v_mfma_f32_32x32x16_bf16 v[32:47], v[68:71], v[166:169], v[32:47]
	v_mfma_f32_32x32x16_bf16 v[16:31], v[68:71], v[174:177], v[16:31]
	v_add_u32_e32 v196, s74, v107
	v_mfma_f32_32x32x16_bf16 v[64:79], v[122:125], v[92:95], 0
	v_add_u32_e32 v197, s74, v108
	v_mfma_f32_32x32x16_bf16 v[64:79], v[132:135], v[88:91], v[64:79]
	v_add_u32_e32 v198, s74, v109
	v_mfma_f32_32x32x16_bf16 v[64:79], v[136:139], v[84:87], v[64:79]
	v_add_u32_e32 v199, s74, v110
	v_mfma_f32_32x32x16_bf16 v[64:79], v[140:143], v[80:83], v[64:79]
	s_setprio 0
	s_cbranch_scc1 .Lhw_d0_b_dtd0bias1
.Lhw_d0_b_n1924:
	ds_read_b128 v[124:127], v196
	ds_read_b128 v[132:135], v197
	ds_read_b128 v[136:139], v198
	ds_read_b128 v[140:143], v199
	ds_read_b64_tr_b16 v[144:145], v121 offset:0x2000
	ds_read_b64_tr_b16 v[146:147], v121 offset:0x2800
	ds_read_b64_tr_b16 v[148:149], v121 offset:0x3000
	ds_read_b64_tr_b16 v[150:151], v121 offset:0x3800
	ds_read_b64_tr_b16 v[152:153], v121 offset:0x2200
	ds_read_b64_tr_b16 v[154:155], v121 offset:0x2a00
	ds_read_b64_tr_b16 v[156:157], v121 offset:0x3200
	ds_read_b64_tr_b16 v[158:159], v121 offset:0x3a00
	ds_read_b64_tr_b16 v[162:163], v121 offset:0x2400
	ds_read_b64_tr_b16 v[164:165], v121 offset:0x2c00
	ds_read_b64_tr_b16 v[166:167], v121 offset:0x3400
	ds_read_b64_tr_b16 v[168:169], v121 offset:0x3c00
	ds_read_b64_tr_b16 v[170:171], v121 offset:0x2600
	ds_read_b64_tr_b16 v[172:173], v121 offset:0x2e00
	ds_read_b64_tr_b16 v[174:175], v121 offset:0x3600
	ds_read_b64_tr_b16 v[176:177], v121 offset:0x3e00
	s_setprio 2
	v_exp_f32_e32 v64, v64
	v_exp_f32_e32 v65, v65
	v_exp_f32_e32 v66, v66
	v_exp_f32_e32 v67, v67
	v_exp_f32_e32 v68, v68
	v_exp_f32_e32 v69, v69
	v_add_f32_e32 v121, v65, v64
	v_exp_f32_e32 v70, v70
	v_add_f32_e32 v121, v66, v121
	v_exp_f32_e32 v71, v71
	v_add_f32_e32 v121, v67, v121
	v_exp_f32_e32 v72, v72
	v_add_f32_e32 v121, v68, v121
	v_exp_f32_e32 v73, v73
	v_add_f32_e32 v121, v69, v121
	v_exp_f32_e32 v74, v74
	v_add_f32_e32 v121, v70, v121
	v_exp_f32_e32 v75, v75
	v_add_f32_e32 v121, v71, v121
	v_exp_f32_e32 v76, v76
	v_add_f32_e32 v121, v72, v121
	v_exp_f32_e32 v77, v77
	v_add_f32_e32 v121, v73, v121
	v_exp_f32_e32 v78, v78
	v_add_f32_e32 v121, v74, v121
	v_exp_f32_e32 v79, v79
	v_add_f32_e32 v121, v75, v121
	v_add_f32_e32 v121, v76, v121
	v_add_f32_e32 v121, v77, v121
	v_add_f32_e32 v121, v78, v121
	v_add_f32_e32 v121, v79, v121
	v_add_f32_e32 v120, v120, v121
	v_cvt_pk_bf16_f32 v64, v64, v65
	v_cvt_pk_bf16_f32 v65, v66, v67
	v_cvt_pk_bf16_f32 v66, v68, v69
	v_cvt_pk_bf16_f32 v67, v70, v71
	v_cvt_pk_bf16_f32 v68, v72, v73
	v_cvt_pk_bf16_f32 v69, v74, v75
	v_cvt_pk_bf16_f32 v70, v76, v77
	v_cvt_pk_bf16_f32 v71, v78, v79
	s_waitcnt lgkmcnt(0)
	s_setprio 1
	s_waitcnt vmcnt(3)
	s_barrier
	v_mfma_f32_32x32x16_bf16 v[0:15], v[64:67], v[144:147], v[0:15]
	s_sub_i32 s74, s0, s55
	s_cmp_lt_u32 s74, s100
	v_mfma_f32_32x32x16_bf16 v[48:63], v[64:67], v[152:155], v[48:63]
	v_mfma_f32_32x32x16_bf16 v[32:47], v[64:67], v[162:165], v[32:47]
	v_mfma_f32_32x32x16_bf16 v[16:31], v[64:67], v[170:173], v[16:31]
	v_mfma_f32_32x32x16_bf16 v[0:15], v[68:71], v[148:151], v[0:15]
	v_mfma_f32_32x32x16_bf16 v[48:63], v[68:71], v[156:159], v[48:63]
	v_mfma_f32_32x32x16_bf16 v[32:47], v[68:71], v[166:169], v[32:47]
	v_mfma_f32_32x32x16_bf16 v[16:31], v[68:71], v[174:177], v[16:31]
	v_lshl_add_u32 v121, s64, 14, v106
	v_mfma_f32_32x32x16_bf16 v[64:79], v[124:127], v[92:95], 0
	v_add_u32_e32 v100, s8, v100
	v_mfma_f32_32x32x16_bf16 v[64:79], v[132:135], v[88:91], v[64:79]
	v_add_u32_e32 v102, s8, v102
	v_mfma_f32_32x32x16_bf16 v[64:79], v[136:139], v[84:87], v[64:79]
	v_add_u32_e32 v104, s8, v104
	v_mfma_f32_32x32x16_bf16 v[64:79], v[140:143], v[80:83], v[64:79]
	s_cbranch_scc1 .Lhw_d0_b_dtd0bias2
.Lhw_d0_b_n1926:
	s_addk_i32 s22, 0x2000
	s_add_i32 s0, s0, 1
	s_add_u32 s7, s7, 0x100
	s_cbranch_scc1 .LBB0_1928
	s_mov_b32 s23, s64
	s_mov_b32 s64, s96
	s_mov_b32 s96, s1
	s_branch .Lhw_d0_b_n1920

.Lhw_d0_b_dtd0bias2:
	v_add_u32_e32 v122, s7, v119
	v_add_u32_e32 v136, 0x28988, v122
	v_add_u32_e32 v138, 0x289a0, v122
	v_add_u32_e32 v140, 0x289a8, v122
	v_add_u32_e32 v123, 0x289c0, v122
	v_add_u32_e32 v124, 0x289c8, v122
	v_add_u32_e32 v126, 0x289e0, v122
	v_add_u32_e32 v132, 0x289e8, v122
	v_add_u32_e32 v121, 0x28980, v122
	ds_read2_b32 v[122:123], v123 offset1:1
	ds_read2_b32 v[124:125], v124 offset1:1
	ds_read2_b32 v[126:127], v126 offset1:1
	ds_read2_b32 v[132:133], v132 offset1:1
	ds_read2_b32 v[134:135], v121 offset1:1
	ds_read2_b32 v[136:137], v136 offset1:1
	ds_read2_b32 v[138:139], v138 offset1:1
	ds_read2_b32 v[140:141], v140 offset1:1
	s_waitcnt lgkmcnt(0)
	v_pk_add_f32 v[78:79], v[78:79], v[132:133]
	v_pk_add_f32 v[76:77], v[76:77], v[126:127]
	v_pk_add_f32 v[74:75], v[74:75], v[124:125]
	v_pk_add_f32 v[72:73], v[72:73], v[122:123]
	v_pk_add_f32 v[70:71], v[70:71], v[140:141]
	v_pk_add_f32 v[68:69], v[68:69], v[138:139]
	v_pk_add_f32 v[66:67], v[66:67], v[136:137]
	v_pk_add_f32 v[64:65], v[64:65], v[134:135]
	v_lshl_add_u32 v121, s64, 14, v106
	s_branch .Lhw_d0_b_n1926

.LBB0_1924:
	ds_read_b128 v[124:127], v196
	ds_read_b128 v[132:135], v197
	ds_read_b128 v[136:139], v198
	ds_read_b128 v[140:143], v199
	ds_read_b64_tr_b16 v[144:145], v121 offset:0x2000
	ds_read_b64_tr_b16 v[146:147], v121 offset:0x2800
	ds_read_b64_tr_b16 v[148:149], v121 offset:0x3000
	ds_read_b64_tr_b16 v[150:151], v121 offset:0x3800
	ds_read_b64_tr_b16 v[152:153], v121 offset:0x2200
	ds_read_b64_tr_b16 v[154:155], v121 offset:0x2a00
	ds_read_b64_tr_b16 v[156:157], v121 offset:0x3200
	ds_read_b64_tr_b16 v[158:159], v121 offset:0x3a00
	ds_read_b64_tr_b16 v[162:163], v121 offset:0x2400
	ds_read_b64_tr_b16 v[164:165], v121 offset:0x2c00
	ds_read_b64_tr_b16 v[166:167], v121 offset:0x3400
	ds_read_b64_tr_b16 v[168:169], v121 offset:0x3c00
	ds_read_b64_tr_b16 v[170:171], v121 offset:0x2600
	ds_read_b64_tr_b16 v[172:173], v121 offset:0x2e00
	ds_read_b64_tr_b16 v[174:175], v121 offset:0x3600
	ds_read_b64_tr_b16 v[176:177], v121 offset:0x3e00
	s_setprio 2
	v_exp_f32_e32 v64, v64
	v_exp_f32_e32 v65, v65
	v_exp_f32_e32 v66, v66
	v_exp_f32_e32 v67, v67
	v_exp_f32_e32 v68, v68
	v_exp_f32_e32 v69, v69
	v_add_f32_e32 v121, v65, v64
	v_exp_f32_e32 v70, v70
	v_add_f32_e32 v121, v66, v121
	v_exp_f32_e32 v71, v71
	v_add_f32_e32 v121, v67, v121
	v_exp_f32_e32 v72, v72
	v_add_f32_e32 v121, v68, v121
	v_exp_f32_e32 v73, v73
	v_add_f32_e32 v121, v69, v121
	v_exp_f32_e32 v74, v74
	v_add_f32_e32 v121, v70, v121
	v_exp_f32_e32 v75, v75
	v_add_f32_e32 v121, v71, v121
	v_exp_f32_e32 v76, v76
	v_add_f32_e32 v121, v72, v121
	v_exp_f32_e32 v77, v77
	v_add_f32_e32 v121, v73, v121
	v_exp_f32_e32 v78, v78
	v_add_f32_e32 v121, v74, v121
	v_exp_f32_e32 v79, v79
	v_add_f32_e32 v121, v75, v121
	v_add_f32_e32 v121, v76, v121
	v_add_f32_e32 v121, v77, v121
	v_add_f32_e32 v121, v78, v121
	v_add_f32_e32 v121, v79, v121
	v_add_f32_e32 v120, v120, v121
	v_cvt_pk_bf16_f32 v64, v64, v65
	v_cvt_pk_bf16_f32 v65, v66, v67
	v_cvt_pk_bf16_f32 v66, v68, v69
	v_cvt_pk_bf16_f32 v67, v70, v71
	v_cvt_pk_bf16_f32 v68, v72, v73
	v_cvt_pk_bf16_f32 v69, v74, v75
	v_cvt_pk_bf16_f32 v70, v76, v77
	v_cvt_pk_bf16_f32 v71, v78, v79
	s_waitcnt lgkmcnt(0)
	s_setprio 1
	v_mfma_f32_32x32x16_bf16 v[0:15], v[64:67], v[144:147], v[0:15]
	s_sub_i32 s74, s0, s55
	s_cmp_lt_u32 s74, s100
	v_mfma_f32_32x32x16_bf16 v[48:63], v[64:67], v[152:155], v[48:63]
	v_mfma_f32_32x32x16_bf16 v[32:47], v[64:67], v[162:165], v[32:47]
	v_mfma_f32_32x32x16_bf16 v[16:31], v[64:67], v[170:173], v[16:31]
	v_mfma_f32_32x32x16_bf16 v[0:15], v[68:71], v[148:151], v[0:15]
	v_mfma_f32_32x32x16_bf16 v[48:63], v[68:71], v[156:159], v[48:63]
	v_mfma_f32_32x32x16_bf16 v[32:47], v[68:71], v[166:169], v[32:47]
	v_mfma_f32_32x32x16_bf16 v[16:31], v[68:71], v[174:177], v[16:31]
	v_lshl_add_u32 v121, s64, 14, v106
	v_mfma_f32_32x32x16_bf16 v[64:79], v[124:127], v[92:95], 0
	v_add_u32_e32 v100, s8, v100
	v_mfma_f32_32x32x16_bf16 v[64:79], v[132:135], v[88:91], v[64:79]
	v_add_u32_e32 v102, s8, v102
	v_mfma_f32_32x32x16_bf16 v[64:79], v[136:139], v[84:87], v[64:79]
	v_add_u32_e32 v104, s8, v104
	v_mfma_f32_32x32x16_bf16 v[64:79], v[140:143], v[80:83], v[64:79]
	s_cbranch_scc1 .Ldt_d0_bias2

; DI float bf2f(unsigned short h) { return __uint_as_float((unsigned)h << 16); }
; template <int DQK, int MODE, int LDQ, int LDK, int LDV> ...
;     ...
;     float l_reg = 0.f; f32x16 o[4];
; #pragma unroll
;     for (int d = 0; d < 4; ++d)
; #pragma unroll
;         for (int r = 0; r < 16; ++r) o[d][r] = 0.f;
;     int kgo[NKP], vgo[2];
; #pragma unroll
;     for (int i = 0; i < NKP; ++i) { const int L = (wid + 8 * i) * 64 + lane, row = L / CPR, slot = L % CPR, cc = (slot & ~7) | ((slot & 7) ^ ((row >> 1) & 7)); kgo[i] = row * LDK + cc * 8; }
; #pragma unroll
;     for (int i = 0; i < 2; ++i) { const int L = (2 * wid + i) * 64 + lane, st = L >> 5, w5 = L & 31, kk = (st >> 2) * 8 + (w5 >> 2), c = (st & 3) * 32 + (w5 & 3) * 8;
;         const int k = (kk & ~0xC) | ((kk & 4) << 1) | ((kk & 8) >> 1); vgo[i] = k * LDV + c; }
;     ...
;     ATT_DMA_K(0); ATT_DMA_K(1); ATT_DMA_V(0, 0); ATT_DMA_K(2); ATT_DMA_V(1, 1);
;     bf16x8 qr[ND0];
;     { const bf16_t* Qw = Qb + (size_t)(wid * 32 + r32) * LDQ + hi * 8;
; #pragma unroll
;       for (int d0 = 0; d0 < ND0; ++d0) qr[d0] = *(const bf16x8*)(Qw + d0 * 16);
;       if constexpr (MODE == 0) {
;           float ss = 0.f;
; #pragma unroll
;           for (int d0 = 0; d0 < ND0; ++d0)
; #pragma unroll
;               for (int j = 0; j < 8; ++j) { const float f = bf2f((unsigned short)qr[d0][j]); ss += f * f; }
;           ss = swap_sum(ss);
;           const float rstd = rsqrtf(ss * (1.f / DQK) + EPS) * C;
; #pragma unroll
;           for (int d0 = 0; d0 < ND0; ++d0) { const float* g = gq + d0 * 16 + hi * 8;
;               { float f[8]; _Pragma("unroll") for (int j = 0; j < 8; ++j) f[j] = bf2f((unsigned short)qr[d0][j]) * rstd * g[j];
;                 u32x4 w = {cvtpk(f[0], f[1]), cvtpk(f[2], f[3]), cvtpk(f[4], f[5]), cvtpk(f[6], f[7])}; qr[d0] = __builtin_bit_cast(bf16x8, w); asm volatile("" ::: "memory"); } }
;       } }
;     const int qlo = q0 + wid * 32, qpos = qlo + r32;
;     const int tL = MODE == 0 ? 0 : (qlo >= 191 ? (qlo - 127) >> 6 : 0), tR = MODE == 0 ? NT : min(NT, (qlo + 222) >> 6);
;     float fL = 1.f, fR = 1.f; if constexpr (MODE != 0) { fL = __builtin_amdgcn_exp2f(bt[0]); fR = __builtin_amdgcn_exp2f(-bt[448]); }
;     ...
;     const int vbase = (int)(unsigned)(size_t)lds + V_OFF + v_rd_base(lane);
.LBB0_1950:
	s_and_b32 s44, s0, 0xffffffc0
	s_min_i32 s52, s45, 64
	s_cmp_gt_i32 s47, 0
	s_cselect_b64 s[4:5], -1, 0
	s_add_i32 s92, s92, s46
	s_add_u32 s6, s79, s90
	s_addc_u32 s7, s80, s91
	s_add_i32 s3, s3, s2
	v_lshl_add_u64 v[100:101], v[0:1], 1, s[6:7]
	v_subrev_u32_e32 v100, s34, v100
	v_add3_u32 v0, s3, v6, v4
	v_lshl_or_b32 v0, v0, 11, v3
	v_and_b32_e32 v7, 63, v7
	v_add_u32_e32 v0, v0, v5
	s_add_u32 s2, s77, s90
	v_exp_f32_e32 v112, v9
	v_lshlrev_b32_e32 v8, 3, v7
	v_lshlrev_b32_e32 v9, 4, v7
	v_lshlrev_b32_e32 v7, 1, v7
	v_ashrrev_i32_e32 v1, 31, v0
	s_addc_u32 s3, s78, s91
	v_exp_f32_e64 v113, -v10
	v_and_b32_e32 v7, 32, v7
	v_add_lshl_u32 v2, s92, v2, 2
	v_lshl_add_u64 v[102:103], v[0:1], 1, s[2:3]
	v_subrev_u32_e32 v102, s34, v102
	v_add_u32_e32 v0, 64, v0
	v_and_b32_e32 v9, 0xc0, v9
	v_and_or_b32 v7, v8, s66, v7
	v_sub_u32_e32 v2, v130, v2
	v_ashrrev_i32_e32 v1, 31, v0
	v_mov_b32_e32 v14, v131
	v_mov_b32_e32 v15, v131
	v_add3_u32 v106, v9, s93, v7
	v_add_u32_e32 v119, 0, v2
	v_lshl_add_u64 v[104:105], v[0:1], 1, s[2:3]
	v_subrev_u32_e32 v104, s34, v104
	v_mov_b32_e32 v0, v131
	v_mov_b32_e32 v1, v131
	v_mov_b32_e32 v2, v131
	v_mov_b32_e32 v3, v131
	v_mov_b32_e32 v4, v131
	v_mov_b32_e32 v5, v131
	v_mov_b32_e32 v6, v131
	v_mov_b32_e32 v7, v131
	v_mov_b32_e32 v8, v131
	v_mov_b32_e32 v9, v131
	v_mov_b32_e32 v10, v131
	v_mov_b32_e32 v11, v131
	v_mov_b32_e32 v12, v131
	v_mov_b32_e32 v13, v131
	v_mov_b64_e32 v[62:63], v[14:15]
	v_mov_b64_e32 v[30:31], v[14:15]
	v_mov_b64_e32 v[46:47], v[14:15]
	s_mov_b32 s0, 1
	s_mov_b32 s62, 0
	s_mov_b32 s1, 2
	s_sub_i32 s53, 0, s47
	s_sub_i32 s6, 0, s52
	v_mov_b32_e32 v120, 0
	s_movk_i32 s7, 0xc300
	s_movk_i32 s22, 0x6000
	s_add_i32 s98, s47, 1
	s_add_i32 s99, s52, 1
	s_sub_i32 s101, s52, s47
	s_max_i32 s100, s101, 0
	v_mov_b32_e32 v196, v107
	v_mov_b32_e32 v197, v108
	v_mov_b32_e32 v198, v109
	v_mov_b32_e32 v199, v110
	v_mov_b64_e32 v[60:61], v[12:13]
	v_mov_b64_e32 v[58:59], v[10:11]
	v_mov_b64_e32 v[56:57], v[8:9]
	v_mov_b64_e32 v[54:55], v[6:7]
	v_mov_b64_e32 v[52:53], v[4:5]
	v_mov_b64_e32 v[50:51], v[2:3]
	v_mov_b64_e32 v[48:49], v[0:1]
	v_mov_b64_e32 v[28:29], v[12:13]
	v_mov_b64_e32 v[26:27], v[10:11]
	v_mov_b64_e32 v[24:25], v[8:9]
	v_mov_b64_e32 v[22:23], v[6:7]
	v_mov_b64_e32 v[20:21], v[4:5]
	v_mov_b64_e32 v[18:19], v[2:3]
	v_mov_b64_e32 v[16:17], v[0:1]
	v_mov_b64_e32 v[44:45], v[12:13]
	v_mov_b64_e32 v[42:43], v[10:11]
	v_mov_b64_e32 v[40:41], v[8:9]
	v_mov_b64_e32 v[38:39], v[6:7]
	v_mov_b64_e32 v[36:37], v[4:5]
	v_mov_b64_e32 v[34:35], v[2:3]
	v_mov_b64_e32 v[32:33], v[0:1]
	s_mov_b32 s49, 1
	v_mov_b32_e32 v121, v106
	s_cmp_lt_u32 s33, 0x100
	s_cbranch_scc1 .LBB0_1951
	s_waitcnt vmcnt(3)
	s_barrier

; #define LAS __attribute__((address_space(3)))
; DI void expsum(f32x16& p, float& l_reg, bf16x8& pa0, bf16x8& pa1) {
; #pragma unroll
;     for (int r = 0; r < 16; ++r) p[r] = __builtin_amdgcn_exp2f(p[r]);
;     float ps = 0.f;
; #pragma unroll
;     for (int r = 0; r < 16; ++r) ps += p[r];
;     l_reg += ps; asm volatile("" : "+v"(l_reg));
;     ...
;     ATT_PK4(p, 0, pa0); ATT_PK4(p, 8, pa1);
;     ...
; }
; DI int v_rd_base(int lane) { return ((lane & 3) << 3) | (((lane >> 2) & 3) << 6) | (((lane >> 4) & 1) << 5) | (((lane >> 5) & 1) << 8); }
; template <int OFF> DI s16x4 tr_read(int vb) { s16x4 r; asm volatile("ds_read_b64_tr_b16 %0, %1 offset:%2" : "=&v"(r) : "v"(vb), "i"(OFF) : "memory"); return r; }
; template <int H> DI void v_reads(s16x4* vf, int vb) {
;     vf[0] = tr_read<v_rd_off(0, 2 * H, 0)>(vb); vf[1] = tr_read<v_rd_off(0, 2 * H, 1)>(vb); vf[2] = tr_read<v_rd_off(0, 2 * H + 1, 0)>(vb); vf[3] = tr_read<v_rd_off(0, 2 * H + 1, 1)>(vb);
;     vf[4] = tr_read<v_rd_off(1, 2 * H, 0)>(vb); vf[5] = tr_read<v_rd_off(1, 2 * H, 1)>(vb); vf[6] = tr_read<v_rd_off(1, 2 * H + 1, 0)>(vb); vf[7] = tr_read<v_rd_off(1, 2 * H + 1, 1)>(vb);
;     vf[8] = tr_read<v_rd_off(2, 2 * H, 0)>(vb); vf[9] = tr_read<v_rd_off(2, 2 * H, 1)>(vb); vf[10] = tr_read<v_rd_off(2, 2 * H + 1, 0)>(vb); vf[11] = tr_read<v_rd_off(2, 2 * H + 1, 1)>(vb);
;     vf[12] = tr_read<v_rd_off(3, 2 * H, 0)>(vb); vf[13] = tr_read<v_rd_off(3, 2 * H, 1)>(vb); vf[14] = tr_read<v_rd_off(3, 2 * H + 1, 0)>(vb); vf[15] = tr_read<v_rd_off(3, 2 * H + 1, 1)>(vb);
; }
; DI void pv_mma(f32x16* o, const s16x4* vf, bf16x8 pa0, bf16x8 pa1) {
;     ...
; #pragma unroll
;     for (int d0 = 0; d0 < 4; ++d0) {
;         o[d0] = __builtin_amdgcn_mfma_f32_32x32x16_bf16(pa0, ATT_PK(vf[4 * d0], vf[4 * d0 + 1]), o[d0], 0, 0, 0);
;         o[d0] = __builtin_amdgcn_mfma_f32_32x32x16_bf16(pa1, ATT_PK(vf[4 * d0 + 2], vf[4 * d0 + 3]), o[d0], 0, 0, 0); }
;     ...
; }
; template <int DQK, int D0A, int D0B> DI void k_reads(bf16x8* kf, const LAS unsigned char* Ks, int half, int r32, int hi) {
; #pragma unroll
;     for (int d0 = D0A; d0 < D0B; ++d0) kf[d0 - D0A] = *(const LAS bf16x8*)(Ks + half * (32 * DQK * 2) + kswz<DQK>(r32, (d0 * 16 + hi * 8) * 2));
; }
; template <int D0A, int D0B> DI void qk_mma(f32x16& p, const bf16x8* kf, const bf16x8* qr) {
; #pragma unroll
;     for (int d0 = D0A; d0 < D0B; ++d0) {
.Lhw_d1_b_n1953:
	ds_read_b128 v[122:125], v196 offset:4096
	ds_read_b128 v[132:135], v197 offset:4096
	s_lshl_b32 s2, s23, 14
	ds_read_b128 v[136:139], v198 offset:4096
	ds_read_b128 v[140:143], v199 offset:4096
	ds_read_b64_tr_b16 v[144:145], v121 offset:0
	ds_read_b64_tr_b16 v[146:147], v121 offset:0x800
	ds_read_b64_tr_b16 v[148:149], v121 offset:0x1000
	ds_read_b64_tr_b16 v[150:151], v121 offset:0x1800
	ds_read_b64_tr_b16 v[152:153], v121 offset:0x200
	ds_read_b64_tr_b16 v[154:155], v121 offset:0xa00
	ds_read_b64_tr_b16 v[156:157], v121 offset:0x1200
	ds_read_b64_tr_b16 v[158:159], v121 offset:0x1a00
	ds_read_b64_tr_b16 v[162:163], v121 offset:0x400
	ds_read_b64_tr_b16 v[164:165], v121 offset:0xc00
	ds_read_b64_tr_b16 v[166:167], v121 offset:0x1400
	ds_read_b64_tr_b16 v[168:169], v121 offset:0x1c00
	ds_read_b64_tr_b16 v[170:171], v121 offset:0x600
	ds_read_b64_tr_b16 v[172:173], v121 offset:0xe00
	ds_read_b64_tr_b16 v[174:175], v121 offset:0x1600
	ds_read_b64_tr_b16 v[176:177], v121 offset:0x1e00
	s_setprio 2
	v_exp_f32_e32 v64, v64
	v_exp_f32_e32 v65, v65
	v_exp_f32_e32 v66, v66
	v_exp_f32_e32 v67, v67
	v_exp_f32_e32 v68, v68
	v_exp_f32_e32 v69, v69
	v_add_f32_e32 v126, v65, v64
	v_exp_f32_e32 v70, v70
	v_add_f32_e32 v126, v66, v126
	v_exp_f32_e32 v71, v71
	v_add_f32_e32 v126, v67, v126
	v_exp_f32_e32 v72, v72
	v_add_f32_e32 v126, v68, v126
	v_exp_f32_e32 v73, v73
	v_add_f32_e32 v126, v69, v126
	v_exp_f32_e32 v74, v74
	v_add_f32_e32 v126, v70, v126
	v_exp_f32_e32 v75, v75
	v_add_f32_e32 v126, v71, v126
	v_exp_f32_e32 v76, v76
	v_add_f32_e32 v126, v72, v126
	v_exp_f32_e32 v77, v77
	v_add_f32_e32 v126, v73, v126
	v_exp_f32_e32 v78, v78
	v_add_f32_e32 v126, v74, v126
	v_exp_f32_e32 v79, v79
	v_add_f32_e32 v126, v75, v126
	v_add_f32_e32 v126, v76, v126
	v_add_f32_e32 v126, v77, v126
	v_add_f32_e32 v126, v78, v126
	v_add_f32_e32 v126, v79, v126
	v_add_f32_e32 v120, v126, v120
	v_cvt_pk_bf16_f32 v64, v64, v65
	v_cvt_pk_bf16_f32 v65, v66, v67
	v_cvt_pk_bf16_f32 v66, v68, v69
	v_cvt_pk_bf16_f32 v67, v70, v71
	v_cvt_pk_bf16_f32 v68, v72, v73
	v_cvt_pk_bf16_f32 v69, v74, v75
	v_cvt_pk_bf16_f32 v70, v76, v77
	v_cvt_pk_bf16_f32 v71, v78, v79
	s_waitcnt lgkmcnt(0)
	s_setprio 1
	v_mfma_f32_32x32x16_bf16 v[0:15], v[64:67], v[144:147], v[0:15]
	s_add_i32 s74, s22, 0xffffc000
	s_and_b32 s74, s74, 0x6000
	s_sub_i32 s3, s0, s98
	s_cmp_lt_u32 s3, s100
	v_mfma_f32_32x32x16_bf16 v[48:63], v[64:67], v[152:155], v[48:63]
	v_mfma_f32_32x32x16_bf16 v[16:31], v[64:67], v[162:165], v[16:31]
	v_mfma_f32_32x32x16_bf16 v[32:47], v[64:67], v[170:173], v[32:47]
	v_mfma_f32_32x32x16_bf16 v[0:15], v[68:71], v[148:151], v[0:15]
	v_mfma_f32_32x32x16_bf16 v[48:63], v[68:71], v[156:159], v[48:63]
	v_mfma_f32_32x32x16_bf16 v[16:31], v[68:71], v[166:169], v[16:31]
	v_mfma_f32_32x32x16_bf16 v[32:47], v[68:71], v[174:177], v[32:47]
	v_add_u32_e32 v196, s74, v107
	v_mfma_f32_32x32x16_bf16 v[64:79], v[122:125], v[92:95], 0
	v_add_u32_e32 v197, s74, v108
	v_mfma_f32_32x32x16_bf16 v[64:79], v[132:135], v[88:91], v[64:79]
	v_add_u32_e32 v198, s74, v109
	v_mfma_f32_32x32x16_bf16 v[64:79], v[136:139], v[84:87], v[64:79]
	v_add_u32_e32 v199, s74, v110
	v_mfma_f32_32x32x16_bf16 v[64:79], v[140:143], v[80:83], v[64:79]
	s_setprio 0
	s_cbranch_scc1 .Lhw_d1_b_dtd1bias1
.Lhw_d1_b_n1955:
	ds_read_b128 v[124:127], v196
	ds_read_b128 v[132:135], v197
	ds_read_b128 v[136:139], v198
	ds_read_b128 v[140:143], v199
	ds_read_b64_tr_b16 v[144:145], v121 offset:0x2000
	ds_read_b64_tr_b16 v[146:147], v121 offset:0x2800
	ds_read_b64_tr_b16 v[148:149], v121 offset:0x3000
	ds_read_b64_tr_b16 v[150:151], v121 offset:0x3800
	ds_read_b64_tr_b16 v[152:153], v121 offset:0x2200
	ds_read_b64_tr_b16 v[154:155], v121 offset:0x2a00
	ds_read_b64_tr_b16 v[156:157], v121 offset:0x3200
	ds_read_b64_tr_b16 v[158:159], v121 offset:0x3a00
	ds_read_b64_tr_b16 v[162:163], v121 offset:0x2400
	ds_read_b64_tr_b16 v[164:165], v121 offset:0x2c00
	ds_read_b64_tr_b16 v[166:167], v121 offset:0x3400
	ds_read_b64_tr_b16 v[168:169], v121 offset:0x3c00
	ds_read_b64_tr_b16 v[170:171], v121 offset:0x2600
	ds_read_b64_tr_b16 v[172:173], v121 offset:0x2e00
	ds_read_b64_tr_b16 v[174:175], v121 offset:0x3600
	ds_read_b64_tr_b16 v[176:177], v121 offset:0x3e00
	s_setprio 2
	v_exp_f32_e32 v64, v64
	v_exp_f32_e32 v65, v65
	v_exp_f32_e32 v66, v66
	v_exp_f32_e32 v67, v67
	v_exp_f32_e32 v68, v68
	v_exp_f32_e32 v69, v69
	v_add_f32_e32 v121, v65, v64
	v_exp_f32_e32 v70, v70
	v_add_f32_e32 v121, v66, v121
	v_exp_f32_e32 v71, v71
	v_add_f32_e32 v121, v67, v121
	v_exp_f32_e32 v72, v72
	v_add_f32_e32 v121, v68, v121
	v_exp_f32_e32 v73, v73
	v_add_f32_e32 v121, v69, v121
	v_exp_f32_e32 v74, v74
	v_add_f32_e32 v121, v70, v121
	v_exp_f32_e32 v75, v75
	v_add_f32_e32 v121, v71, v121
	v_exp_f32_e32 v76, v76
	v_add_f32_e32 v121, v72, v121
	v_exp_f32_e32 v77, v77
	v_add_f32_e32 v121, v73, v121
	v_exp_f32_e32 v78, v78
	v_add_f32_e32 v121, v74, v121
	v_exp_f32_e32 v79, v79
	v_add_f32_e32 v121, v75, v121
	v_add_f32_e32 v121, v76, v121
	v_add_f32_e32 v121, v77, v121
	v_add_f32_e32 v121, v78, v121
	v_add_f32_e32 v121, v79, v121
	v_add_f32_e32 v120, v120, v121
	v_cvt_pk_bf16_f32 v64, v64, v65
	v_cvt_pk_bf16_f32 v65, v66, v67
	v_cvt_pk_bf16_f32 v66, v68, v69
	v_cvt_pk_bf16_f32 v67, v70, v71
	v_cvt_pk_bf16_f32 v68, v72, v73
	v_cvt_pk_bf16_f32 v69, v74, v75
	v_cvt_pk_bf16_f32 v70, v76, v77
	v_cvt_pk_bf16_f32 v71, v78, v79
	s_waitcnt lgkmcnt(0)
	s_setprio 1
	s_waitcnt vmcnt(3)
	s_barrier
	v_mfma_f32_32x32x16_bf16 v[0:15], v[64:67], v[144:147], v[0:15]
	s_sub_i32 s74, s0, s47
	s_cmp_lt_u32 s74, s100
	v_mfma_f32_32x32x16_bf16 v[48:63], v[64:67], v[152:155], v[48:63]
	v_mfma_f32_32x32x16_bf16 v[16:31], v[64:67], v[162:165], v[16:31]
	v_mfma_f32_32x32x16_bf16 v[32:47], v[64:67], v[170:173], v[32:47]
	v_mfma_f32_32x32x16_bf16 v[0:15], v[68:71], v[148:151], v[0:15]
	v_mfma_f32_32x32x16_bf16 v[48:63], v[68:71], v[156:159], v[48:63]
	v_mfma_f32_32x32x16_bf16 v[16:31], v[68:71], v[166:169], v[16:31]
	v_mfma_f32_32x32x16_bf16 v[32:47], v[68:71], v[174:177], v[32:47]
	v_lshl_add_u32 v121, s49, 14, v106
	v_mfma_f32_32x32x16_bf16 v[64:79], v[124:127], v[92:95], 0
	v_add_u32_e32 v100, s8, v100
	v_mfma_f32_32x32x16_bf16 v[64:79], v[132:135], v[88:91], v[64:79]
	v_add_u32_e32 v102, s8, v102
	v_mfma_f32_32x32x16_bf16 v[64:79], v[136:139], v[84:87], v[64:79]
	v_add_u32_e32 v104, s8, v104
	v_mfma_f32_32x32x16_bf16 v[64:79], v[140:143], v[80:83], v[64:79]
	s_cbranch_scc1 .Lhw_d1_b_dtd1bias2
.Lhw_d1_b_n1957:
	s_addk_i32 s22, 0x2000
	s_add_i32 s0, s0, 1
	s_add_u32 s7, s7, 0x100
	s_cbranch_scc1 .LBB0_1959
	s_mov_b32 s62, s49
	s_mov_b32 s49, s1
	s_mov_b32 s1, s23
	s_branch .Lhw_d1_b_n1951

.Lhw_d1_b_dtd1bias2:
	v_add_u32_e32 v122, s7, v119
	v_add_u32_e32 v136, 0x28988, v122
	v_add_u32_e32 v138, 0x289a0, v122
	v_add_u32_e32 v140, 0x289a8, v122
	v_add_u32_e32 v123, 0x289c0, v122
	v_add_u32_e32 v124, 0x289c8, v122
	v_add_u32_e32 v126, 0x289e0, v122
	v_add_u32_e32 v132, 0x289e8, v122
	v_add_u32_e32 v121, 0x28980, v122
	ds_read2_b32 v[122:123], v123 offset1:1
	ds_read2_b32 v[124:125], v124 offset1:1
	ds_read2_b32 v[126:127], v126 offset1:1
	ds_read2_b32 v[132:133], v132 offset1:1
	ds_read2_b32 v[134:135], v121 offset1:1
	ds_read2_b32 v[136:137], v136 offset1:1
	ds_read2_b32 v[138:139], v138 offset1:1
	ds_read2_b32 v[140:141], v140 offset1:1
	s_waitcnt lgkmcnt(0)
	v_pk_add_f32 v[78:79], v[78:79], v[132:133]
	v_pk_add_f32 v[76:77], v[76:77], v[126:127]
	v_pk_add_f32 v[74:75], v[74:75], v[124:125]
	v_pk_add_f32 v[72:73], v[72:73], v[122:123]
	v_pk_add_f32 v[70:71], v[70:71], v[140:141]
	v_pk_add_f32 v[68:69], v[68:69], v[138:139]
	v_pk_add_f32 v[66:67], v[66:67], v[136:137]
	v_pk_add_f32 v[64:65], v[64:65], v[134:135]
	v_lshl_add_u32 v121, s49, 14, v106
	s_branch .Lhw_d1_b_n1957

; #define LAS __attribute__((address_space(3)))
; DI void expsum(f32x16& p, float& l_reg, bf16x8& pa0, bf16x8& pa1) {
; #pragma unroll
;     for (int r = 0; r < 16; ++r) p[r] = __builtin_amdgcn_exp2f(p[r]);
;     float ps = 0.f;
; #pragma unroll
;     for (int r = 0; r < 16; ++r) ps += p[r];
;     l_reg += ps; asm volatile("" : "+v"(l_reg));
;     ...
;     ATT_PK4(p, 0, pa0); ATT_PK4(p, 8, pa1);
;     ...
; }
; DI int v_rd_base(int lane) { return ((lane & 3) << 3) | (((lane >> 2) & 3) << 6) | (((lane >> 4) & 1) << 5) | (((lane >> 5) & 1) << 8); }
; template <int OFF> DI s16x4 tr_read(int vb) { s16x4 r; asm volatile("ds_read_b64_tr_b16 %0, %1 offset:%2" : "=&v"(r) : "v"(vb), "i"(OFF) : "memory"); return r; }
; template <int H> DI void v_reads(s16x4* vf, int vb) {
;     vf[0] = tr_read<v_rd_off(0, 2 * H, 0)>(vb); vf[1] = tr_read<v_rd_off(0, 2 * H, 1)>(vb); vf[2] = tr_read<v_rd_off(0, 2 * H + 1, 0)>(vb); vf[3] = tr_read<v_rd_off(0, 2 * H + 1, 1)>(vb);
;     vf[4] = tr_read<v_rd_off(1, 2 * H, 0)>(vb); vf[5] = tr_read<v_rd_off(1, 2 * H, 1)>(vb); vf[6] = tr_read<v_rd_off(1, 2 * H + 1, 0)>(vb); vf[7] = tr_read<v_rd_off(1, 2 * H + 1, 1)>(vb);
;     vf[8] = tr_read<v_rd_off(2, 2 * H, 0)>(vb); vf[9] = tr_read<v_rd_off(2, 2 * H, 1)>(vb); vf[10] = tr_read<v_rd_off(2, 2 * H + 1, 0)>(vb); vf[11] = tr_read<v_rd_off(2, 2 * H + 1, 1)>(vb);
;     vf[12] = tr_read<v_rd_off(3, 2 * H, 0)>(vb); vf[13] = tr_read<v_rd_off(3, 2 * H, 1)>(vb); vf[14] = tr_read<v_rd_off(3, 2 * H + 1, 0)>(vb); vf[15] = tr_read<v_rd_off(3, 2 * H + 1, 1)>(vb);
; }
; DI void pv_mma(f32x16* o, const s16x4* vf, bf16x8 pa0, bf16x8 pa1) {
;     ...
; #pragma unroll
;     for (int d0 = 0; d0 < 4; ++d0) {
;         o[d0] = __builtin_amdgcn_mfma_f32_32x32x16_bf16(pa0, ATT_PK(vf[4 * d0], vf[4 * d0 + 1]), o[d0], 0, 0, 0);
;         o[d0] = __builtin_amdgcn_mfma_f32_32x32x16_bf16(pa1, ATT_PK(vf[4 * d0 + 2], vf[4 * d0 + 3]), o[d0], 0, 0, 0); }
;     ...
; }
; template <int DQK, int D0A, int D0B> DI void k_reads(bf16x8* kf, const LAS unsigned char* Ks, int half, int r32, int hi) {
; #pragma unroll
;     for (int d0 = D0A; d0 < D0B; ++d0) kf[d0 - D0A] = *(const LAS bf16x8*)(Ks + half * (32 * DQK * 2) + kswz<DQK>(r32, (d0 * 16 + hi * 8) * 2));
; }
; template <int D0A, int D0B> DI void qk_mma(f32x16& p, const bf16x8* kf, const bf16x8* qr) {
; #pragma unroll
;     for (int d0 = D0A; d0 < D0B; ++d0) {
.LBB0_1955:
	ds_read_b128 v[124:127], v196
	ds_read_b128 v[132:135], v197
	ds_read_b128 v[136:139], v198
	ds_read_b128 v[140:143], v199
	ds_read_b64_tr_b16 v[144:145], v121 offset:0x2000
	ds_read_b64_tr_b16 v[146:147], v121 offset:0x2800
	ds_read_b64_tr_b16 v[148:149], v121 offset:0x3000
	ds_read_b64_tr_b16 v[150:151], v121 offset:0x3800
	ds_read_b64_tr_b16 v[152:153], v121 offset:0x2200
	ds_read_b64_tr_b16 v[154:155], v121 offset:0x2a00
	ds_read_b64_tr_b16 v[156:157], v121 offset:0x3200
	ds_read_b64_tr_b16 v[158:159], v121 offset:0x3a00
	ds_read_b64_tr_b16 v[162:163], v121 offset:0x2400
	ds_read_b64_tr_b16 v[164:165], v121 offset:0x2c00
	ds_read_b64_tr_b16 v[166:167], v121 offset:0x3400
	ds_read_b64_tr_b16 v[168:169], v121 offset:0x3c00
	ds_read_b64_tr_b16 v[170:171], v121 offset:0x2600
	ds_read_b64_tr_b16 v[172:173], v121 offset:0x2e00
	ds_read_b64_tr_b16 v[174:175], v121 offset:0x3600
	ds_read_b64_tr_b16 v[176:177], v121 offset:0x3e00
	s_setprio 2
	v_exp_f32_e32 v64, v64
	v_exp_f32_e32 v65, v65
	v_exp_f32_e32 v66, v66
	v_exp_f32_e32 v67, v67
	v_exp_f32_e32 v68, v68
	v_exp_f32_e32 v69, v69
	v_add_f32_e32 v121, v65, v64
	v_exp_f32_e32 v70, v70
	v_add_f32_e32 v121, v66, v121
	v_exp_f32_e32 v71, v71
	v_add_f32_e32 v121, v67, v121
	v_exp_f32_e32 v72, v72
	v_add_f32_e32 v121, v68, v121
	v_exp_f32_e32 v73, v73
	v_add_f32_e32 v121, v69, v121
	v_exp_f32_e32 v74, v74
	v_add_f32_e32 v121, v70, v121
	v_exp_f32_e32 v75, v75
	v_add_f32_e32 v121, v71, v121
	v_exp_f32_e32 v76, v76
	v_add_f32_e32 v121, v72, v121
	v_exp_f32_e32 v77, v77
	v_add_f32_e32 v121, v73, v121
	v_exp_f32_e32 v78, v78
	v_add_f32_e32 v121, v74, v121
	v_exp_f32_e32 v79, v79
	v_add_f32_e32 v121, v75, v121
	v_add_f32_e32 v121, v76, v121
	v_add_f32_e32 v121, v77, v121
	v_add_f32_e32 v121, v78, v121
	v_add_f32_e32 v121, v79, v121
	v_add_f32_e32 v120, v120, v121
	v_cvt_pk_bf16_f32 v64, v64, v65
	v_cvt_pk_bf16_f32 v65, v66, v67
	v_cvt_pk_bf16_f32 v66, v68, v69
	v_cvt_pk_bf16_f32 v67, v70, v71
	v_cvt_pk_bf16_f32 v68, v72, v73
	v_cvt_pk_bf16_f32 v69, v74, v75
	v_cvt_pk_bf16_f32 v70, v76, v77
	v_cvt_pk_bf16_f32 v71, v78, v79
	s_waitcnt lgkmcnt(0)
	s_setprio 1
	v_mfma_f32_32x32x16_bf16 v[0:15], v[64:67], v[144:147], v[0:15]
	s_sub_i32 s74, s0, s47
	s_cmp_lt_u32 s74, s100
	v_mfma_f32_32x32x16_bf16 v[48:63], v[64:67], v[152:155], v[48:63]
	v_mfma_f32_32x32x16_bf16 v[16:31], v[64:67], v[162:165], v[16:31]
	v_mfma_f32_32x32x16_bf16 v[32:47], v[64:67], v[170:173], v[32:47]
	v_mfma_f32_32x32x16_bf16 v[0:15], v[68:71], v[148:151], v[0:15]
	v_mfma_f32_32x32x16_bf16 v[48:63], v[68:71], v[156:159], v[48:63]
	v_mfma_f32_32x32x16_bf16 v[16:31], v[68:71], v[166:169], v[16:31]
	v_mfma_f32_32x32x16_bf16 v[32:47], v[68:71], v[174:177], v[32:47]
	v_lshl_add_u32 v121, s49, 14, v106
	v_mfma_f32_32x32x16_bf16 v[64:79], v[124:127], v[92:95], 0
	v_add_u32_e32 v100, s8, v100
	v_mfma_f32_32x32x16_bf16 v[64:79], v[132:135], v[88:91], v[64:79]
	v_add_u32_e32 v102, s8, v102
	v_mfma_f32_32x32x16_bf16 v[64:79], v[136:139], v[84:87], v[64:79]
	v_add_u32_e32 v104, s8, v104
	v_mfma_f32_32x32x16_bf16 v[64:79], v[140:143], v[80:83], v[64:79]
	s_cbranch_scc1 .Ldt_d1_bias2
